# v1 + forget-gate cumsum moved to workgroups 200-215 + out-proj unit order rotated by 64 workgroups (phase load balance)
# speedup vs baseline: 1.0049x; 1.0049x over previous
; __device__ __forceinline__ int lane_id_v() { int l; asm volatile("v_mbcnt_lo_u32_b32 %0, -1, 0\n\tv_mbcnt_hi_u32_b32 %0, -1, %0" : "=v"(l)); return l; }
; #define WSB() unsigned char* wsb_ = ws; int blk = (int)blockIdx.x, Gs = G, wvl = wave; asm volatile("" : "+s"(wsb_), "+s"(blk), "+s"(Gs), "+s"(wvl)); GAS unsigned char* wsb = (GAS unsigned char*)wsb_
; __global__ void __launch_bounds__(512, 2) hybrid_fwd(Args args) {
;     ...
;             if (gw < CB * 8) {
;                 WSB(); const int lane = lane_id_v();
;                 const int b = gw >> 3, h = gw & 7; const float bf = b_f[l * 8 + h];
;                 const int p0 = 33 * lane;
.LBB0_244:
	v_writelane_b32 v254, s66, 24
	s_or_b64 exec, exec, s[0:1]
	s_add_u32 s78, s94, 0x2200
	s_addc_u32 s79, s95, 0
	s_add_u32 s66, s94, 0x2400
	s_addc_u32 s67, s95, 0
	s_add_u32 s70, s94, 0x2500
	s_addc_u32 s71, s95, 0
	s_add_u32 s2, s94, 0x2600
	s_addc_u32 s3, s95, 0
	s_add_u32 s0, s94, 0x2700
	s_addc_u32 s1, s95, 0
	v_writelane_b32 v254, s0, 25
	s_mov_b32 s49, 0
	v_writelane_b32 v255, s93, 0
	v_writelane_b32 v254, s1, 26
	s_add_u32 s0, s94, 0x2800
	s_addc_u32 s1, s95, 0
	v_writelane_b32 v254, s0, 27
	s_movk_i32 s33, 0x80
	v_mov_b32_e32 v19, 0
	v_writelane_b32 v254, s1, 28
	s_add_u32 s0, s94, 0x2900
	s_addc_u32 s1, s95, 0
	v_writelane_b32 v254, s0, 29
	s_movk_i32 s63, 0x3c0
	v_mov_b32_e32 v200, 0x358637bd
	v_writelane_b32 v254, s1, 30
	s_add_u32 s0, s94, 0x2a00
	s_addc_u32 s1, s95, 0
	v_writelane_b32 v254, s0, 31
	s_movk_i32 s40, 0x3600
	v_mov_b32_e32 v201, 1
	v_writelane_b32 v254, s1, 32
	s_add_u32 s0, s94, 0x2b00
	s_addc_u32 s1, s95, 0
	v_writelane_b32 v254, s0, 33
	s_movk_i32 s61, 0x50
	s_mov_b32 s54, 0x41a00000
	v_writelane_b32 v254, s1, 34
	s_add_u32 s0, s94, 0x2c00
	s_addc_u32 s1, s95, 0
	v_writelane_b32 v254, s0, 35
	v_mov_b32_e32 v204, 0xfffffd00
	v_mov_b32_e32 v205, 0xf149f2ca
	v_writelane_b32 v254, s1, 36
	s_add_u32 s0, s94, 0x2d00
	s_addc_u32 s1, s95, 0
	v_writelane_b32 v254, s0, 37
	v_mov_b32_e32 v206, 0x42800000
	s_waitcnt lgkmcnt(0)
	v_mov_b32_e32 v0, 1.0
	v_writelane_b32 v254, s1, 38
	s_add_u32 s0, s94, 0x2e00
	s_addc_u32 s1, s95, 0
	v_writelane_b32 v254, s0, 39
	s_mov_b64 s[50:51], 0x80
	s_mov_b32 s20, s49
	v_writelane_b32 v254, s1, 40
	s_add_u32 s0, s94, 0x2f00
	s_addc_u32 s1, s95, 0
	v_writelane_b32 v254, s0, 41
	s_brev_b32 s44, 1
	s_nop 0
	v_writelane_b32 v254, s1, 42
	s_add_u32 s0, s94, 0x3000
	s_addc_u32 s1, s95, 0
	v_writelane_b32 v254, s0, 43
	s_barrier
	s_nop 0
	v_writelane_b32 v254, s1, 44
	s_add_u32 s0, s94, 0x3100
	s_addc_u32 s1, s95, 0
	v_writelane_b32 v254, s0, 45
	s_nop 1
	v_writelane_b32 v254, s1, 46
	s_add_u32 s0, s94, 0x3200
	s_addc_u32 s1, s95, 0
	v_writelane_b32 v254, s0, 47
	s_nop 1
	v_writelane_b32 v254, s1, 48
	s_add_u32 s0, s94, 0x3300
	s_addc_u32 s1, s95, 0
	v_writelane_b32 v254, s0, 49
	s_nop 1
	v_writelane_b32 v254, s1, 50
	s_add_u32 s0, s94, 0x5400
	s_addc_u32 s1, s95, 0
	v_writelane_b32 v254, s0, 51
	s_nop 1
	v_writelane_b32 v254, s1, 52
	s_add_u32 s0, s94, 0x5500
	s_addc_u32 s1, s95, 0
	v_writelane_b32 v254, s0, 53
	s_add_i32 s0, s68, 0xfffff9c0
	s_cmp_lt_u32 s0, 0x80
	v_writelane_b32 v255, s94, 1
	v_writelane_b32 v254, s1, 54
	s_cselect_b64 s[0:1], -1, 0
	v_writelane_b32 v255, s95, 2
	v_writelane_b32 v254, s0, 55
	v_writelane_b32 v255, s96, 3
	v_writelane_b32 v255, s97, 4
	v_writelane_b32 v254, s1, 56
	s_mov_b32 s0, s68
	v_writelane_b32 v254, s0, 57
	v_writelane_b32 v255, s78, 5
	s_add_i32 s43, 0, 0x20000
	v_writelane_b32 v254, s1, 58
	s_add_i32 s0, s68, 0xfffff9c0
	s_ashr_i32 s0, s0, 3
	s_bfe_u32 s1, s60, 0x30006
	v_writelane_b32 v255, s79, 6
	v_writelane_b32 v254, s1, 59
	s_lshl_b32 s1, s0, 11
	v_writelane_b32 v255, s66, 7
	s_add_i32 s1, s1, -16
	s_lshl_b32 s0, s0, 4
	v_writelane_b32 v255, s67, 8
	v_writelane_b32 v254, s1, 60
	s_add_i32 s0, s0, 0x8000
	v_writelane_b32 v255, s70, 9
	s_mov_b64 s[68:69], s[2:3]
	v_writelane_b32 v254, s0, 61
	s_add_i32 s0, 0, 0x20010
	v_writelane_b32 v255, s71, 10
	v_writelane_b32 v254, s0, 62
	s_add_i32 s0, 0, 0x20014
	v_writelane_b32 v255, s68, 11
	v_writelane_b32 v254, s0, 63
	s_movk_i32 s60, 0x1000
	v_writelane_b32 v255, s69, 12
	s_branch .LBB0_246

; #define WSB() unsigned char* wsb_ = ws; int blk = (int)blockIdx.x, Gs = G, wvl = wave; asm volatile("" : "+s"(wsb_), "+s"(blk), "+s"(Gs), "+s"(wvl)); GAS unsigned char* wsb = (GAS unsigned char*)wsb_
;     __device__ bool next(int i, Unit& u) const {
;         const int it = i / NZ; u.z = i - it * NZ;
;         const long L = (long)it * G + c; if (L >= nwg) return false;
;         int wgid = (int)L; { const int q = nwg / NXCD, r = nwg % NXCD, xcd = wgid % NXCD, off = wgid / NXCD; wgid = (xcd < r ? xcd * (q + 1) : r * (q + 1) + (xcd - r) * q) + off; }
;         const int nig = WGM * nN, gid = wgid / nig, fm = gid * WGM, gsz = (nM - fm) < WGM ? (nM - fm) : WGM;
;         u.pm = fm + ((wgid % nig) % gsz); u.pn = (wgid % nig) / gsz; return true;
; __global__ void __launch_bounds__(512, 2) hybrid_fwd(Args args) {
;     ...
;             {
;                 WSB();
;                 pg8::Gemm g{Y, Wout + (size_t)l * 1024 * 1024, Mc, 1024, 1024, 0, 0};
;                 pg8::StaticOrder S; S.init(Mc, 1024, Gs, blk, 1);
;                 EpiOut E{l == 0 ? x_chunk : out_chunk, l == 0 ? meta_tok : XM, l == 0 ? (NMETA - 1) : 0x7fffffff, out_chunk, XM, XB + (size_t)chunk * MC * 1024, SSQX + (size_t)chunk * MC * 16, l < DEPTH - 1};
;                 pg8::gemm_phase(lds, g, S, E, wvl);
.LBB0_966:
	s_or_b64 exec, exec, s[4:5]
	s_mov_b32 s20, s97
	s_mov_b64 s[8:9], s[94:95]
	s_mov_b32 s0, s96
	s_mov_b32 s1, s93
	s_waitcnt lgkmcnt(0)
	s_barrier
	s_add_i32 s1, s1, 64
	s_and_b32 s1, s1, 0xff
	s_cmp_lt_i32 s1, s76
	s_cselect_b64 s[6:7], -1, 0
	s_cmp_ge_i32 s1, s76
	v_mbcnt_lo_u32_b32 v1, -1, 0
	v_mbcnt_hi_u32_b32 v1, -1, v1
	s_cbranch_scc1 .LBB0_972
	s_ashr_i32 s2, s1, 31
	s_lshr_b32 s2, s2, 29
	s_add_i32 s2, s1, s2
	s_and_b32 s3, s2, -8
	s_and_b32 s11, s76, 4
	s_sub_i32 s3, s1, s3
	s_cmp_ge_i32 s3, s11
	s_mov_b64 s[4:5], -1
	s_cbranch_scc0 .LBB0_969
	s_sub_i32 s5, s3, s11
	s_mul_i32 s4, s11, 0x41
	s_lshl_b32 s5, s5, 6
	s_add_i32 s10, s5, s4
	s_mov_b64 s[4:5], 0
